# c8 + pass C (4a,4b): queue fetch (atomic + 2 barriers) moved behind the unit's global loads so the round trips overlap
# baseline (speedup 1.0000x reference)
.LBB0_1113:
	s_cmpk_gt_i32 s30, 0xff
	s_cbranch_scc0 .Lpc4a_d1a
	s_lshl_b32 s0, s30, 3
	s_add_i32 s9, s0, 0x800
	s_branch .LBB0_1127
.Lpc4a_d1a:
	s_lshl_b32 s0, s30, 4
	s_lshl_b32 s1, s30, 3
	s_and_b32 s0, s0, 0xfffff800
	s_and_b32 s1, s1, 0x3f8
	s_or_b32 s9, s0, s1
.LBB0_1127:
	s_or_b32 s4, s9, s54
	s_cmpk_gt_i32 s4, 0xfff
	s_mov_b64 s[6:7], -1
	v_mbcnt_lo_u32_b32 v53, -1, 0
	v_mbcnt_hi_u32_b32 v53, -1, v53
	s_cbranch_scc0 .LBB0_1129
	s_add_i32 s30, s4, 0xfffff000
	s_lshr_b32 s0, s30, 3
	s_lshl_b32 s1, s0, 4
	s_add_i32 s68, s1, 0x8000
	s_mul_hi_u32 s1, s0, 0xd40
	s_mulk_i32 s0, 0xd40
	s_add_u32 s44, s47, s0
	s_addc_u32 s45, s48, s1
	s_lshl_b64 s[0:1], s[30:31], 14
	s_add_u32 s0, s49, s0
	s_addc_u32 s1, s50, s1
	s_mov_b32 s5, s31
	s_mov_b64 s[6:7], 0

.LBB0_1166:
	s_or_b64 exec, exec, s[0:1]
	v_lshlrev_b32_e32 v58, 2, v79
	v_lshlrev_b32_e32 v54, 2, v75
	global_load_dwordx2 v[60:61], v58, s[22:23]
	s_nop 0
	global_load_dwordx2 v[58:59], v54, s[24:25]
	v_ashrrev_i32_e32 v79, 3, v67
	v_and_b32_e32 v56, 56, v56
	v_mul_lo_u32 v79, v79, s62
	v_lshl_add_u32 v56, v56, 2, v79
	s_mov_b64 s[82:83], vcc
	s_and_b64 vcc, exec, s[2:3]
	s_barrier
	s_cbranch_vccnz .Lpc4a_q3
	v_mbcnt_lo_u32_b32 v102, -1, 0
	v_mbcnt_hi_u32_b32 v102, -1, v102
	s_nop 0
	v_cmp_eq_u32_e32 vcc, 0, v102
	s_and_saveexec_b64 s[92:93], vcc
	s_cbranch_execz .Lpc4a_q2
	s_mov_b64 s[96:97], exec
	v_mbcnt_lo_u32_b32 v102, s96, 0
	v_mbcnt_hi_u32_b32 v102, s97, v102
	v_cmp_eq_u32_e32 vcc, 0, v102
	s_and_saveexec_b64 s[94:95], vcc
	s_cbranch_execz .Lpc4a_q1
	s_bcnt1_i32_b64 s96, s[96:97]
	v_mov_b32_e32 v103, s96
	global_atomic_add v103, v55, v103, s[18:19] offset:256 sc0
.Lpc4a_q1:
	s_or_b64 exec, exec, s[94:95]
	s_waitcnt vmcnt(0)
	v_readfirstlane_b32 s94, v103
	s_nop 1
	v_add_u32_e32 v102, s94, v102
	ds_write_b32 v39, v102
.Lpc4a_q2:
	s_or_b64 exec, exec, s[92:93]
.Lpc4a_q3:
	s_waitcnt lgkmcnt(0)
	s_barrier
	ds_read_b32 v102, v39
	s_waitcnt lgkmcnt(0)
	v_readfirstlane_b32 s67, v102
	s_cmpk_gt_i32 s67, 0xff
	s_cbranch_scc0 .Lpc4a_d2a
	s_lshl_b32 s92, s67, 3
	s_add_i32 s92, s92, s17
	s_cmpk_lt_u32 s67, 0x110
	s_cselect_b32 s72, s92, -1
	s_branch .Lpc4a_d2b
.Lpc4a_d2a:
	s_lshl_b32 s92, s67, 4
	s_lshl_b32 s93, s67, 3
	s_and_b32 s92, s92, 0xfffff800
	s_and_b32 s93, s93, 0x3f8
	s_or_b32 s92, s93, s92
	s_or_b32 s72, s92, s54
.Lpc4a_d2b:
	s_mov_b64 vcc, s[82:83]
	s_nop 3
	s_waitcnt vmcnt(4)
	v_lshlrev_b32_e32 v79, 16, v44
	v_lshlrev_b32_e32 v82, 16, v47
	v_and_b32_e32 v44, 0xffff0000, v44
	v_and_b32_e32 v47, 0xffff0000, v47
	v_lshlrev_b32_e32 v80, 16, v45
	v_lshlrev_b32_e32 v81, 16, v46
	v_and_b32_e32 v45, 0xffff0000, v45
	v_and_b32_e32 v46, 0xffff0000, v46
	ds_write2_b32 v56, v82, v47 offset0:6 offset1:7
	ds_write2_b32 v56, v81, v46 offset0:4 offset1:5
	ds_write2_b32 v56, v80, v45 offset0:2 offset1:3
	ds_write2_b32 v56, v79, v44 offset1:1
	v_add_u32_e32 v44, 0x4100, v56
	s_waitcnt vmcnt(2)
	ds_write2_b32 v44, v40, v41 offset1:1
	v_add_u32_e32 v40, 0x4108, v56
	ds_write2_b32 v40, v42, v43 offset1:1
	v_add_u32_e32 v40, 0x4110, v56
	ds_write2_b32 v40, v32, v33 offset1:1
	v_add_u32_e32 v32, 0x4118, v56
	ds_write2_b32 v32, v34, v35 offset1:1
	v_mov_b32_e32 v41, 0
	v_mov_b32_e32 v32, 0
	v_mov_b32_e32 v33, 0
	s_and_saveexec_b64 s[0:1], vcc
	s_cbranch_execz .LBB0_1168
	global_load_dwordx2 v[32:33], v54, s[26:27]

.LBB0_1299:
	s_lshl_b32 s0, s42, 4
	s_and_b32 s9, s0, 0xfffff800
	s_lshl_b32 s0, s42, 3
	s_and_b32 s10, s0, 0x3f8
	s_bitset1_b32 s10, 10
	s_or_b32 s0, s9, s54
	s_or_b32 s0, s0, s10
	s_cmpk_gt_i32 s0, 0xfff
	s_mov_b64 s[6:7], -1
	v_mbcnt_lo_u32_b32 v53, -1, 0
	v_mbcnt_hi_u32_b32 v53, -1, v53
	s_cbranch_scc0 .LBB0_1307
	s_add_i32 s28, s0, 0xfffff000
	s_lshr_b32 s1, s28, 3
	s_lshl_b32 s4, s1, 4
	s_add_i32 s72, s4, 0x8000
	s_mul_hi_u32 s4, s1, 0xd40
	s_mulk_i32 s1, 0xd40
	s_add_u32 s44, s47, s1
	s_addc_u32 s45, s48, s4
	s_lshl_b64 s[4:5], s[28:29], 14
	s_add_u32 s4, s49, s4
	s_addc_u32 s5, s50, s5
	s_mov_b32 s1, s29
	s_mov_b64 s[6:7], 0

.LBB0_1333:
	s_or_b64 exec, exec, s[0:1]
	v_lshlrev_b32_e32 v56, 2, v79
	v_lshlrev_b32_e32 v54, 2, v77
	global_load_dwordx2 v[60:61], v56, s[22:23]
	s_nop 0
	global_load_dwordx2 v[56:57], v54, s[24:25]
	v_ashrrev_i32_e32 v79, 3, v67
	v_and_b32_e32 v58, 56, v58
	v_mul_lo_u32 v79, v79, s62
	v_lshl_add_u32 v58, v58, 2, v79
	s_mov_b64 s[82:83], vcc
	s_and_b64 vcc, exec, s[88:89]
	s_barrier
	s_cbranch_vccnz .Lpc4b_q3
	v_mbcnt_lo_u32_b32 v102, -1, 0
	v_mbcnt_hi_u32_b32 v102, -1, v102
	s_nop 0
	v_cmp_eq_u32_e32 vcc, 0, v102
	s_and_saveexec_b64 s[92:93], vcc
	s_cbranch_execz .Lpc4b_q2
	s_mov_b64 s[96:97], exec
	v_mbcnt_lo_u32_b32 v102, s96, 0
	v_mbcnt_hi_u32_b32 v102, s97, v102
	v_cmp_eq_u32_e32 vcc, 0, v102
	s_and_saveexec_b64 s[94:95], vcc
	s_cbranch_execz .Lpc4b_q1
	s_bcnt1_i32_b64 s96, s[96:97]
	v_mov_b32_e32 v103, s96
	global_atomic_add v103, v55, v103, s[18:19] offset:320 sc0
.Lpc4b_q1:
	s_or_b64 exec, exec, s[94:95]
	s_waitcnt vmcnt(0)
	v_readfirstlane_b32 s94, v103
	s_nop 1
	v_add_u32_e32 v102, s94, v102
	ds_write_b32 v41, v102

.Lpc4b_q3:
	s_waitcnt lgkmcnt(0)
	s_barrier
	ds_read_b32 v102, v41
	s_waitcnt lgkmcnt(0)
	v_readfirstlane_b32 s71, v102
	s_mov_b64 vcc, s[82:83]
	s_nop 3
	s_waitcnt vmcnt(4)
	v_lshlrev_b32_e32 v79, 16, v46
	v_lshlrev_b32_e32 v82, 16, v49
	v_and_b32_e32 v46, 0xffff0000, v46
	v_and_b32_e32 v49, 0xffff0000, v49
	v_lshlrev_b32_e32 v80, 16, v47
	v_lshlrev_b32_e32 v81, 16, v48
	v_and_b32_e32 v47, 0xffff0000, v47
	v_and_b32_e32 v48, 0xffff0000, v48
	ds_write2_b32 v58, v82, v49 offset0:6 offset1:7
	ds_write2_b32 v58, v81, v48 offset0:4 offset1:5
	ds_write2_b32 v58, v80, v47 offset0:2 offset1:3
	ds_write2_b32 v58, v79, v46 offset1:1
	v_add_u32_e32 v46, 0x4100, v58
	s_waitcnt vmcnt(2)
	ds_write2_b32 v46, v42, v43 offset1:1
	v_add_u32_e32 v42, 0x4108, v58
	ds_write2_b32 v42, v44, v45 offset1:1
	v_add_u32_e32 v42, 0x4110, v58
	ds_write2_b32 v42, v36, v37 offset1:1
	v_add_u32_e32 v36, 0x4118, v58
	ds_write2_b32 v36, v38, v39 offset1:1
	v_mov_b32_e32 v43, 0
	v_mov_b32_e32 v36, 0
	v_mov_b32_e32 v37, 0
	s_and_saveexec_b64 s[0:1], vcc
	s_cbranch_execz .LBB0_1335
	global_load_dwordx2 v[36:37], v54, s[26:27]
